# S5 phase: remap workgroup->group pair so the 4 groups sharing a 128B line of U/G are processed on the same XCD (L2 sharing)
# speedup vs baseline: 1.0087x; 1.0087x over previous
.LBB0_150:
	s_and_b32 s55, s33, 0xffffff80
	s_lshr_b32 s2, s72, 3
	s_or_b32 s10, s72, s55
	v_writelane_b32 v253, s2, 7
	s_lshl_b32 s2, s88, 1
	s_ashr_i32 s8, s10, 6
	v_writelane_b32 v253, s2, 8
	s_and_b32 s2, s2, 14
	s_ashr_i32 s9, s8, 31
	v_writelane_b32 v253, s2, 9
	s_ashr_i32 s6, s10, 2
	s_lshl_b64 s[2:3], s[8:9], 17
	v_writelane_b32 v253, s2, 10
	s_ashr_i32 s7, s6, 31
	s_lshl_b64 s[12:13], s[6:7], 19
	v_writelane_b32 v253, s3, 11
	s_lshl_b64 s[2:3], s[6:7], 13
	v_writelane_b32 v253, s2, 12
	s_lshl_b64 s[8:9], s[8:9], 23
	s_ashr_i32 s5, s33, 7
	v_writelane_b32 v253, s3, 13
	s_lshl_b32 s2, s72, 8
	s_and_b32 s11, s2, 0x300
	s_lshl_b32 s2, s11, 8
	s_or_b32 s12, s12, s2
	v_writelane_b32 v253, s12, 14
	s_lshl_b64 s[2:3], s[6:7], 18
	s_lshl_b32 s7, s11, 12
	v_writelane_b32 v253, s13, 15
	v_writelane_b32 v253, s7, 16
	v_writelane_b32 v253, s8, 17
	s_or_b32 s7, s11, 0xc0
	s_lshl_b32 s56, s5, 16
	v_writelane_b32 v253, s9, 18
	v_writelane_b32 v253, s11, 19
	v_writelane_b32 v253, s7, 20
	s_lshl_b32 s7, s72, 9
	s_and_b32 s4, s6, 15
	s_lshl_b32 s6, s6, 7
	s_or_b32 s7, s7, s56
	s_lshl_b32 s60, s5, 4
	s_and_b32 s6, s6, 0x780
	v_writelane_b32 v253, s7, 21
	s_add_i32 s7, s56, 0x10000
	s_add_u32 s58, s0, 0x8560200
	s_addc_u32 s59, s1, 0
	s_add_u32 s62, s0, 0x8560400
	s_addc_u32 s63, s1, 0
	s_add_u32 s64, s0, 0x8560500
	s_addc_u32 s65, s1, 0
	s_add_u32 s70, s0, 0x8560600
	s_addc_u32 s71, s1, 0
	s_add_u32 s80, s0, 0x8560700
	s_addc_u32 s81, s1, 0
	s_add_u32 s86, s0, 0x8560800
	s_addc_u32 s87, s1, 0
	s_add_u32 s90, s0, 0x8560900
	s_addc_u32 s91, s1, 0
	s_add_u32 s94, s0, 0x8560a00
	s_addc_u32 s95, s1, 0
	s_add_u32 s8, s0, 0x8560b00
	v_writelane_b32 v253, s7, 22
	s_addc_u32 s9, s1, 0
	v_writelane_b32 v253, s8, 23
	s_mov_b32 s29, 0
	s_mov_b32 s73, s29
	v_writelane_b32 v253, s9, 24
	s_add_u32 s8, s0, 0x8560c00
	s_addc_u32 s9, s1, 0
	v_writelane_b32 v253, s8, 25
	s_mov_b32 s54, 1
	v_mov_b32_e32 v209, 0
	v_writelane_b32 v253, s9, 26
	s_add_u32 s8, s0, 0x8560d00
	s_addc_u32 s9, s1, 0
	v_writelane_b32 v253, s8, 27
	s_mov_b32 s19, 0x20000
	s_brev_b32 s18, 32
	v_writelane_b32 v253, s9, 28
	s_add_u32 s8, s0, 0x8560e00
	s_addc_u32 s9, s1, 0
	v_writelane_b32 v253, s8, 29
	v_mov_b32_e32 v246, 0xc0135761
	v_mov_b32_e32 v248, 0x1000
	v_writelane_b32 v253, s9, 30
	s_add_u32 s8, s0, 0x8560f00
	s_addc_u32 s9, s1, 0
	v_writelane_b32 v253, s8, 31
	v_mov_b32_e32 v249, 0x2000
	v_mbcnt_hi_u32_b32 v250, -1, v67
	v_writelane_b32 v253, s9, 32
	s_add_u32 s8, s0, 0x8561000
	s_addc_u32 s9, s1, 0
	v_writelane_b32 v253, s8, 33
	v_mov_b32_e32 v251, 0xff800000
	s_mov_b32 s92, 0x800000
	v_writelane_b32 v253, s9, 34
	s_add_u32 s8, s0, 0x8561100
	s_addc_u32 s9, s1, 0
	v_writelane_b32 v253, s8, 35
	s_movk_i32 s93, 0x800
	s_movk_i32 s26, 0xf7ff
	v_writelane_b32 v253, s9, 36
	s_add_u32 s8, s0, 0x8561200
	s_addc_u32 s9, s1, 0
	v_writelane_b32 v253, s8, 37
	s_mov_b32 s27, 0x41000000
	s_movk_i32 s85, 0x7fff
	v_writelane_b32 v253, s9, 38
	s_add_u32 s8, s0, 0x8561300
	s_addc_u32 s9, s1, 0
	v_writelane_b32 v253, s8, 39
	s_mov_b64 s[96:97], 0x80
	s_mov_b64 s[74:75], 0x100
	v_writelane_b32 v253, s9, 40
	s_add_u32 s8, s0, 0x8563400
	s_addc_u32 s9, s1, 0
	v_writelane_b32 v253, s8, 41
	s_add_u32 s0, s0, 0x8563500
	s_addc_u32 s1, s1, 0
	v_writelane_b32 v253, s9, 42
	v_writelane_b32 v253, s0, 43
	s_nop 1
	v_writelane_b32 v253, s1, 44
	s_mul_i32 s0, s5, 0xd80
	s_addk_i32 s0, 0xd80
	s_ashr_i32 s1, s0, 31
	s_lshl_b64 s[0:1], s[0:1], 2
	v_readlane_b32 s5, v253, 4
	s_add_u32 s78, s5, s0
	v_readlane_b32 s0, v253, 5
	s_addc_u32 s79, s0, s1
	s_add_u32 s0, s78, 0x200
	s_addc_u32 s1, s79, 0
	v_writelane_b32 v253, s0, 45
	s_nop 1
	v_writelane_b32 v253, s1, 46
	s_add_u32 s0, s78, 0x1000
	s_addc_u32 s1, s79, 0
	v_writelane_b32 v253, s0, 47
	s_nop 1
	v_writelane_b32 v253, s1, 48
	s_add_u32 s0, s78, 0x1100
	s_addc_u32 s1, s79, 0
	v_writelane_b32 v253, s0, 49
	s_nop 1
	v_writelane_b32 v253, s1, 50
	s_add_u32 s0, s78, 0x1200
	s_addc_u32 s1, s79, 0
	v_writelane_b32 v253, s0, 51
	s_nop 1
	v_writelane_b32 v253, s1, 52
	s_add_u32 s0, s78, 0x1300
	s_addc_u32 s1, s79, 0
	v_writelane_b32 v253, s0, 53
	s_nop 1
	v_writelane_b32 v253, s1, 54
	s_add_u32 s0, s78, 0x3400
	s_addc_u32 s1, s79, 0
	v_writelane_b32 v253, s0, 55
	s_nop 1
	v_writelane_b32 v253, s1, 56
	s_add_u32 s0, s78, 0x3500
	s_addc_u32 s1, s79, 0
	v_writelane_b32 v253, s0, 57
	s_lshl_b64 s[2:3], s[2:3], 1
	s_nop 0
	v_writelane_b32 v253, s1, 58
	s_lshl_b32 s0, s10, 5
	v_writelane_b32 v253, s0, 59
	v_writelane_b32 v253, s10, 60
	s_lshl_b32 s0, s10, 1
	s_lshl_b32 s1, s0, 1
	s_and_b32 s1, s1, 0x1c
	s_lshr_b32 vcc_lo, s0, 3
	s_and_b32 vcc_lo, vcc_lo, 2
	s_or_b32 s1, s1, vcc_lo
	s_andn2_b32 s0, s0, 0x1f
	s_or_b32 s0, s0, s1
	s_nop 1
	v_writelane_b32 v253, s0, 61
	v_writelane_b32 v253, s0, 8
	s_lshl_b32 s0, s4, 2
	v_writelane_b32 v253, s0, 62
	v_writelane_b32 v253, s2, 63
	s_lshl_b32 s0, s6, 1
	s_mov_b32 s1, 0xffff0000
	v_writelane_b32 v254, s3, 0
	v_writelane_b32 v254, s0, 1
	s_add_i32 s0, 0, 0x20000
	v_writelane_b32 v254, s0, 2
	s_add_i32 s0, 0, 0x23fc8
	v_writelane_b32 v254, s0, 3
	s_add_i32 s0, 0, 0x23fcc
	v_writelane_b32 v254, s0, 4
	s_add_i32 s0, 0, 0x23fc0
	v_writelane_b32 v254, s0, 5
	s_add_i32 s0, 0, 0x23fc4
	v_writelane_b32 v254, s0, 6
	v_writelane_b32 v254, s60, 7
	v_writelane_b32 v254, s76, 8
	s_mov_b32 s0, 0x3e0293ee
	s_nop 0
	v_writelane_b32 v254, s77, 9
	v_writelane_b32 v254, s55, 10
	v_writelane_b32 v254, s56, 11
	v_writelane_b32 v254, s58, 12
	s_nop 1
	v_writelane_b32 v254, s59, 13
	v_writelane_b32 v254, s62, 14
	s_nop 1
	v_writelane_b32 v254, s63, 15
	v_writelane_b32 v254, s64, 16
	s_nop 1
	v_writelane_b32 v254, s65, 17
	v_writelane_b32 v254, s70, 18
	s_nop 1
	v_writelane_b32 v254, s71, 19
	v_writelane_b32 v254, s80, 20
	s_nop 1
	v_writelane_b32 v254, s81, 21
	v_writelane_b32 v254, s86, 22
	s_nop 1
	v_writelane_b32 v254, s87, 23
	v_writelane_b32 v254, s90, 24
	s_nop 1
	v_writelane_b32 v254, s91, 25
	v_writelane_b32 v254, s94, 26
	s_nop 1
	v_writelane_b32 v254, s95, 27
	s_branch .LBB0_152
